# p5pipe: rwkv_post prefetches the next trip's five loads one trip ahead (double-buffered registers)
# baseline (speedup 1.0000x reference)
.LBB0_876:
	s_cmp_lt_i32 s92, 6
	s_cselect_b64 s[4:5], -1, 0
	s_and_b64 s[0:1], s[4:5], s[2:3]
	s_andn2_b64 vcc, exec, s[0:1]
	s_cbranch_vccnz .LBB0_883
	v_lshrrev_b32_e32 v0, 4, v170
	v_and_b32_e32 v1, 60, v0
	v_lshl_add_u32 v18, s69, 5, v1
	s_mov_b32 s0, 0x40000
	v_cmp_gt_i32_e32 vcc, s0, v18
	s_and_saveexec_b64 s[6:7], vcc
	s_cbranch_execz .LBB0_882
	s_add_u32 s8, s66, 0x1d000000
	s_addc_u32 s9, s67, 0
	s_add_u32 s10, s66, 0x1f000000
	s_addc_u32 s11, s67, 0
	s_add_u32 s12, s64, 0x5200000
	v_and_b32_e32 v19, 3, v0
	v_lshlrev_b32_e32 v0, 2, v170
	s_addc_u32 s13, s65, 0
	v_and_b32_e32 v20, 60, v0
	s_lshl_b32 s18, s96, 5
	s_mov_b64 s[14:15], 0
	v_mov_b32_e32 v1, 0
	s_movk_i32 s19, 0x3000
	v_mov_b64_e32 v[2:3], s[66:67]
	s_mov_b64 s[16:17], 0xd002420
	v_mov_b32_e32 v21, 0x3a27c5ac
	s_mov_b32 s20, 0x800000
	s_movk_i32 s21, 0x2000
	s_mov_b32 s22, 0x3ffff
	v_and_or_b32 v22, v18, 12, v19
	v_lshl_or_b32 v23, v22, 6, v20
	v_lshlrev_b32_e32 v34, 2, v23
	v_mov_b32_e32 v35, v1
	v_readlane_b32 s40, v235, 27
	v_readlane_b32 s41, v235, 28
	v_readlane_b32 s42, v235, 45
	v_readlane_b32 s43, v235, 46
	v_readlane_b32 s44, v235, 47
	v_readlane_b32 s45, v235, 48
	s_nop 4
	global_load_dwordx4 v[150:153], v34, s[42:43]
	global_load_dwordx4 v[154:157], v34, s[44:45]
	v_lshl_add_u64 v[36:37], s[40:41], 0, v[34:35]
	v_add_co_u32_e32 v34, vcc, s21, v36
	s_nop 1
	v_addc_co_u32_e32 v35, vcc, 0, v37, vcc
	global_load_dwordx4 v[158:161], v[34:35], off
	v_lshlrev_b32_e32 v0, 1, v23
	v_mov_b32_e32 v175, v18
	v_ashrrev_i32_e32 v176, 4, v175
	v_ashrrev_i32_e32 v177, 31, v176
	v_lshlrev_b64 v[178:179], 11, v[176:177]
	v_lshl_add_u64 v[178:179], s[12:13], 0, v[178:179]
	v_lshl_add_u64 v[178:179], v[178:179], 0, v[0:1]
	global_load_dwordx2 v[164:165], v[178:179], off nt
	v_mad_i64_i32 v[178:179], s[2:3], v176, s19, v[2:3]
	v_lshl_add_u64 v[180:181], v[178:179], 0, v[0:1]
	v_add_co_u32_e32 v182, vcc, 0xd002000, v180
	s_nop 1
	v_addc_co_u32_e32 v183, vcc, 0, v181, vcc
	global_load_dwordx2 v[166:167], v[182:183], off offset:1056
	v_lshl_add_u64 v[182:183], v[180:181], 0, s[16:17]
	v_add_co_u32_e32 v182, vcc, 0xffffd000, v182
	s_nop 1
	v_addc_co_u32_e32 v183, vcc, -1, v183, vcc
	global_load_dwordx2 v[168:169], v[182:183], off
	v_lshlrev_b64 v[178:179], 10, v[176:177]
	v_lshl_add_u64 v[178:179], v[178:179], 1, s[8:9]
	v_lshl_add_u64 v[178:179], v[178:179], 0, v[0:1]
	global_load_dwordx2 v[172:173], v[178:179], off nt
	v_lshlrev_b64 v[178:179], 6, v[176:177]
	v_lshl_add_u64 v[178:179], s[10:11], 0, v[178:179]
	v_lshlrev_b32_e32 v180, 2, v22
	v_mov_b32_e32 v181, v1
	v_lshl_add_u64 v[178:179], v[178:179], 0, v[180:181]
	global_load_dword v174, v[178:179], off
	global_load_dword v184, v[178:179], off
	s_branch .LBB0_880
.LBB0_879:
	v_readlane_b32 s36, v235, 23
	v_readlane_b32 s37, v235, 24
	v_readlane_b32 s38, v235, 25
	v_readlane_b32 s39, v235, 26
	v_readlane_b32 s40, v235, 27
	v_readlane_b32 s41, v235, 28
	v_readlane_b32 s42, v235, 29
	v_readlane_b32 s43, v235, 30
	v_readlane_b32 s44, v235, 31
	v_readlane_b32 s45, v235, 32
	v_readlane_b32 s46, v235, 33
	v_readlane_b32 s47, v235, 34
	v_readlane_b32 s48, v235, 35
	v_readlane_b32 s49, v235, 36
	v_readlane_b32 s50, v235, 37
	v_readlane_b32 s51, v235, 38
	v_readlane_b32 s36, v235, 39
	v_readlane_b32 s42, v235, 45
	v_readlane_b32 s43, v235, 46
	v_readlane_b32 s44, v235, 47
	v_readlane_b32 s45, v235, 48
	s_nop 0
	s_nop 2
	s_nop 0
	v_add_f32_e32 v23, v24, v25
	v_lshlrev_b64 v[4:5], 13, v[4:5]
	v_fmamk_f32 v23, v23, 0x3c800000, v21
	v_sub_co_u32_e32 v4, vcc, 0, v4
	v_mul_f32_e32 v40, 0x4b800000, v23
	s_nop 0
	v_subb_co_u32_e32 v5, vcc, 0, v5, vcc
	v_cmp_gt_f32_e64 s[2:3], s20, v23
	v_lshl_add_u64 v[4:5], v[6:7], 0, v[4:5]
	v_lshl_add_u64 v[4:5], v[4:5], 0, v[0:1]
	v_cndmask_b32_e64 v6, v23, v40, s[2:3]
	v_rsq_f32_e32 v0, v6
	v_cndmask_b32_e64 v162, 0, v162, s[0:1]
	v_cndmask_b32_e64 v163, 0, v163, s[0:1]
	v_lshlrev_b32_e32 v24, 16, v12
	v_and_b32_e32 v25, 0xffff0000, v12
	v_lshlrev_b32_e32 v38, 16, v162
	v_mul_f32_e32 v6, 0x45800000, v0
	v_and_b32_e32 v39, 0xffff0000, v162
	v_lshlrev_b32_e32 v12, 16, v13
	v_and_b32_e32 v13, 0xffff0000, v13
	v_lshlrev_b32_e32 v14, 16, v163
	v_and_b32_e32 v15, 0xffff0000, v163
	v_cndmask_b32_e64 v0, v0, v6, s[2:3]
	v_pk_add_f32 v[38:39], v[38:39], v[24:25] neg_lo:[0,1] neg_hi:[0,1]
	v_pk_add_f32 v[14:15], v[14:15], v[12:13] neg_lo:[0,1] neg_hi:[0,1]
	v_pk_mul_f32 v[6:7], v[8:9], v[0:1] op_sel_hi:[1,0]
	v_pk_mul_f32 v[8:9], v[10:11], v[0:1] op_sel_hi:[1,0]
	v_add_u32_e32 v18, s18, v18
	v_cmp_lt_i32_e64 s[0:1], s22, v18
	v_add_co_u32_e32 v4, vcc, 0x9000000, v4
	s_or_b64 s[14:15], s[0:1], s[14:15]
	s_nop 0
	v_addc_co_u32_e32 v5, vcc, 0, v5, vcc
	v_readlane_b32 s37, v235, 40
	v_readlane_b32 s38, v235, 41
	v_readlane_b32 s39, v235, 42
	v_readlane_b32 s40, v235, 43
	v_readlane_b32 s41, v235, 44
	v_readlane_b32 s46, v235, 49
	v_readlane_b32 s47, v235, 50
	v_readlane_b32 s48, v235, 51
	v_readlane_b32 s49, v235, 52
	v_readlane_b32 s50, v235, 53
	v_readlane_b32 s51, v235, 54
	v_lshlrev_b32_e32 v10, 16, v142
	v_and_b32_e32 v11, 0xffff0000, v142
	v_lshlrev_b32_e32 v16, 16, v143
	v_and_b32_e32 v17, 0xffff0000, v143
	v_pk_fma_f32 v[6:7], v[6:7], v[150:151], v[154:155]
	v_pk_fma_f32 v[8:9], v[8:9], v[152:153], v[156:157]
	v_pk_fma_f32 v[24:25], v[158:159], v[38:39], v[24:25]
	v_pk_fma_f32 v[12:13], v[14:15], v[160:161], v[12:13]
	v_pk_fma_f32 v[6:7], v[148:149], v[24:25], v[6:7] op_sel_hi:[0,1,1]
	v_pk_fma_f32 v[8:9], v[148:149], v[12:13], v[8:9] op_sel_hi:[0,1,1]
	v_pk_mul_f32 v[6:7], v[6:7], v[10:11]
	v_pk_mul_f32 v[8:9], v[8:9], v[16:17]
	v_cvt_pk_bf16_f32 v6, v6, v7
	v_cvt_pk_bf16_f32 v7, v8, v9
	global_store_dwordx2 v[4:5], v[6:7], off offset:2048
	s_andn2_b64 exec, exec, s[14:15]
	s_cbranch_execz .LBB0_882
.LBB0_880:
	s_waitcnt vmcnt(1)
	v_ashrrev_i32_e32 v4, 4, v18
	v_and_or_b32 v22, v18, 12, v19
	v_ashrrev_i32_e32 v5, 31, v4
	v_lshl_or_b32 v23, v22, 6, v20
	v_lshlrev_b64 v[6:7], 11, v[4:5]
	v_lshl_add_u64 v[6:7], s[12:13], 0, v[6:7]
	v_lshlrev_b32_e32 v0, 1, v23
	v_lshl_add_u64 v[6:7], v[6:7], 0, v[0:1]
	v_mov_b32_e32 v8, v164
	v_mov_b32_e32 v9, v165
	v_mad_i64_i32 v[6:7], s[0:1], v4, s19, v[2:3]
	v_lshl_add_u64 v[16:17], v[6:7], 0, v[0:1]
	v_add_co_u32_e32 v10, vcc, 0xd002000, v16
	v_mov_b32_e32 v14, v1
	s_nop 0
	v_addc_co_u32_e32 v11, vcc, 0, v17, vcc
	v_mov_b32_e32 v12, v166
	v_mov_b32_e32 v13, v167
	v_mov_b32_e32 v162, v168
	v_mov_b32_e32 v163, v169
	v_mov_b32_e32 v142, v172
	v_mov_b32_e32 v143, v173
	v_mov_b32_e32 v148, v174
	v_add_u32_e32 v175, s18, v18
	v_cmp_lt_i32_e64 s[2:3], s22, v175
	s_nop 1
	v_cndmask_b32_e64 v175, v175, v18, s[2:3]
	v_ashrrev_i32_e32 v176, 4, v175
	v_ashrrev_i32_e32 v177, 31, v176
	v_lshlrev_b64 v[178:179], 11, v[176:177]
	v_lshl_add_u64 v[178:179], s[12:13], 0, v[178:179]
	v_lshl_add_u64 v[178:179], v[178:179], 0, v[0:1]
	global_load_dwordx2 v[164:165], v[178:179], off nt
	v_mad_i64_i32 v[178:179], s[2:3], v176, s19, v[2:3]
	v_lshl_add_u64 v[180:181], v[178:179], 0, v[0:1]
	v_add_co_u32_e32 v182, vcc, 0xd002000, v180
	s_nop 1
	v_addc_co_u32_e32 v183, vcc, 0, v181, vcc
	global_load_dwordx2 v[166:167], v[182:183], off offset:1056
	v_lshl_add_u64 v[182:183], v[180:181], 0, s[16:17]
	v_add_co_u32_e32 v182, vcc, 0xffffd000, v182
	s_nop 1
	v_addc_co_u32_e32 v183, vcc, -1, v183, vcc
	global_load_dwordx2 v[168:169], v[182:183], off
	v_lshlrev_b64 v[178:179], 10, v[176:177]
	v_lshl_add_u64 v[178:179], v[178:179], 1, s[8:9]
	v_lshl_add_u64 v[178:179], v[178:179], 0, v[0:1]
	global_load_dwordx2 v[172:173], v[178:179], off nt
	v_lshlrev_b64 v[178:179], 6, v[176:177]
	v_lshl_add_u64 v[178:179], s[10:11], 0, v[178:179]
	v_lshlrev_b32_e32 v180, 2, v22
	v_mov_b32_e32 v181, v1
	v_lshl_add_u64 v[178:179], v[178:179], 0, v[180:181]
	global_load_dword v174, v[178:179], off
	v_and_b32_e32 v10, 0xfff0, v18
	v_cmp_ne_u32_e32 vcc, 0, v10
	v_lshlrev_b32_e32 v10, 16, v9
	v_and_b32_e32 v11, 0xffff0000, v9
	v_lshlrev_b32_e32 v24, 16, v8
	v_and_b32_e32 v25, 0xffff0000, v8
	v_mov_b32_e32 v8, v24
	v_mov_b32_e32 v9, v10
	v_mov_b32_e32 v26, v25
	v_mov_b32_e32 v27, v11
	v_pk_add_f32 v[8:9], v[8:9], v[26:27]
	s_nop 0
	v_add_f32_e32 v8, v8, v9
	s_nop 1
	v_add_f32_dpp v8, v8, v8 quad_perm:[1,0,3,2] row_mask:0xf bank_mask:0xf bound_ctrl:1
	s_nop 1
	v_add_f32_dpp v8, v8, v8 quad_perm:[2,3,0,1] row_mask:0xf bank_mask:0xf bound_ctrl:1
	s_nop 1
	v_add_f32_dpp v8, v8, v8 row_half_mirror row_mask:0xf bank_mask:0xf bound_ctrl:1
	s_nop 1
	v_add_f32_dpp v8, v8, v8 row_mirror row_mask:0xf bank_mask:0xf bound_ctrl:1
	v_mul_f32_e32 v26, 0x3c800000, v8
	v_pk_add_f32 v[8:9], v[24:25], v[26:27] op_sel_hi:[1,0] neg_lo:[0,1] neg_hi:[0,1]
	v_pk_add_f32 v[10:11], v[10:11], v[26:27] op_sel_hi:[1,0] neg_lo:[0,1] neg_hi:[0,1]
	v_pk_mul_f32 v[24:25], v[8:9], v[8:9]
	v_pk_mul_f32 v[26:27], v[10:11], v[10:11]
	v_add_f32_e32 v15, v24, v25
	v_add_f32_e32 v15, v26, v15
	v_add_f32_e32 v15, v27, v15
	s_nop 1
	v_add_f32_dpp v15, v15, v15 quad_perm:[1,0,3,2] row_mask:0xf bank_mask:0xf bound_ctrl:1
	s_nop 1
	v_add_f32_dpp v15, v15, v15 quad_perm:[2,3,0,1] row_mask:0xf bank_mask:0xf bound_ctrl:1
	s_nop 1
	v_add_f32_dpp v24, v15, v15 row_half_mirror row_mask:0xf bank_mask:0xf bound_ctrl:1
	v_mov_b32_e32 v15, v1
	s_nop 0
	v_mov_b32_dpp v25, v24 row_mirror row_mask:0xf bank_mask:0xf bound_ctrl:1
	s_mov_b64 s[0:1], vcc
	s_branch .LBB0_879
